# attention tile loop unrolled x2: loop-invariant K/Kr fragment addresses, buffer chosen by ds_read immediate offset (no per-k-step xor)
# speedup vs baseline: 1.0015x; 1.0015x over previous
; #define SBAR() __builtin_amdgcn_sched_barrier(0)
; #define QK_RD(d0, sl) do { if ((d0) < 8) { const int a_ = kbase ^ (((d0) & 7) << 5); KRD(f0[sl], a_, 0); KRD(f1[sl], a_, 32 * 256); } \
;                            else { const int a_ = rbase ^ (((d0) & 3) << 5); KRD(f0[sl], a_, 0); KRD(f1[sl], a_, 32 * 128); } } while (0)
; #define PV_RD(d0, L, H) do { constexpr int b_ = v_rd_off(d0, 0, 0); TRRD(L[0], b_); TRRD(H[0], b_ + 2048); TRRD(L[1], b_ + 4096); TRRD(H[1], b_ + 6144); TRRD(L[2], b_ + 8192); TRRD(H[2], b_ + 10240); TRRD(L[3], b_ + 12288); TRRD(H[3], b_ + 14336); } while (0)
; #define LGKM(n) asm volatile("s_waitcnt lgkmcnt(" #n ")" ::: "memory")
; __device__ __forceinline__ void mphase(bool has_pv, f32x16* o, int vb, bf16x8 pa0, bf16x8 pa1, bf16x8 pa2, bf16x8 pa3, f32x16& p0, f32x16& p1, int kbase, int rbase, const bf16x8* qr) {
;     bf16x8 f0[3], f1[3];
;     ...
;     if (has_pv) {
;         s16x4 la[4], ha[4], lb[4], hb[4];
;         PV_RD(0, la, ha); PV_RD(1, lb, hb);
;         LGKM(8); SBAR(); PV_MM(0, la, ha); SBAR();
;         PV_RD(2, la, ha); LGKM(8); SBAR(); PV_MM(1, lb, hb); SBAR();
;         PV_RD(3, lb, hb); LGKM(8); SBAR(); PV_MM(2, la, ha); SBAR();
;         LGKM(0); SBAR(); PV_MM(3, lb, hb); SBAR();
;     }
;     QK_RD(0, 0); QK_RD(1, 1);
; __device__ __forceinline__ void attn_block(const Ptrs& P, int b, int h, int qb, LAS char* lds) {
;     ...
;     float m_reg = -1e30f, l_reg = 0.f; f32x16 o[4] = {};
;     bf16x8 st_k0, st_k1, st_v0, st_v1, st_r;
;     const unsigned gofk = (unsigned)((tid >> 4) * 128 + (tid & 15) * 8) * 2u, gofr = (unsigned)((tid >> 3) * 64 + (tid & 7) * 8) * 2u;
;     ...
;     SLOAD(0); SWRITE(0, 0);
; #pragma unroll
;     for (int d0 = 0; d0 < 12; ++d0) asm volatile("" :: "v"(qr[d0]) : "memory");
;     if (NT > 1) SLOAD(1);
;     __syncthreads();
;     int ts = 1 + grp, ts3 = 1 + grp;
;     if (grp) {
;         if (NT > 1) SWRITE(1, 1);
;         if (NT > 2) SLOAD(2);
;         __syncthreads(); }
;     f32x16 p0, p1; bf16x8 pa0, pa1, pa2, pa3;
;     int pv3 = 0;
;     ...
;     for (int x = 0; x < NT; ++x) {
;         SBAR(); __builtin_amdgcn_s_setprio(1);
;         mphase(x > 0, o, vb0 + pv3 * SHM_V, pa0, pa1, pa2, pa3, p0, p1, kbase, rbase, qr); if (x > 0) pv3 = pv3 == 2 ? 0 : pv3 + 1;
.LBB0_614:
	s_and_b32 s39, s38, 0x3fffffc0
	s_lshl_b32 s39, s39, 2
	s_add_i32 s39, s39, 0
	v_mov_b32_e32 v16, v2
	v_mov_b32_e32 v17, v2
	s_xor_b64 s[36:37], s[22:23], -1
	s_add_i32 s22, s74, 0x10f
	s_add_i32 s39, s39, 0x18000
	s_lshr_b32 s38, s38, 8
	v_mov_b32_e32 v3, v2
	v_mov_b32_e32 v4, v2
	v_mov_b32_e32 v5, v2
	v_mov_b32_e32 v6, v2
	v_mov_b32_e32 v7, v2
	v_mov_b32_e32 v8, v2
	v_mov_b32_e32 v9, v2
	v_mov_b32_e32 v10, v2
	v_mov_b32_e32 v11, v2
	v_mov_b32_e32 v12, v2
	v_mov_b32_e32 v13, v2
	v_mov_b32_e32 v14, v2
	v_mov_b32_e32 v15, v2
	v_mov_b64_e32 v[66:67], v[16:17]
	v_mov_b64_e32 v[50:51], v[16:17]
	v_mov_b64_e32 v[34:35], v[16:17]
	s_add_i32 s23, s6, s74
	s_add_i32 s77, s38, 1
	v_lshl_add_u32 v194, v174, 2, s39
	v_lshl_add_u32 v193, v181, 2, s39
	s_lshl_b32 s39, s38, 13
	s_lshl_b32 s38, s38, 14
	s_and_b32 s80, s22, 0x1fc0
	v_mov_b64_e32 v[64:65], v[14:15]
	v_mov_b64_e32 v[62:63], v[12:13]
	v_mov_b64_e32 v[60:61], v[10:11]
	v_mov_b64_e32 v[58:59], v[8:9]
	v_mov_b64_e32 v[56:57], v[6:7]
	v_mov_b64_e32 v[54:55], v[4:5]
	v_mov_b64_e32 v[52:53], v[2:3]
	v_mov_b64_e32 v[48:49], v[14:15]
	v_mov_b64_e32 v[46:47], v[12:13]
	v_mov_b64_e32 v[44:45], v[10:11]
	v_mov_b64_e32 v[42:43], v[8:9]
	v_mov_b64_e32 v[40:41], v[6:7]
	v_mov_b64_e32 v[38:39], v[4:5]
	v_mov_b64_e32 v[36:37], v[2:3]
	v_mov_b64_e32 v[32:33], v[14:15]
	v_mov_b64_e32 v[30:31], v[12:13]
	v_mov_b64_e32 v[28:29], v[10:11]
	v_mov_b64_e32 v[26:27], v[8:9]
	v_mov_b64_e32 v[24:25], v[6:7]
	v_mov_b64_e32 v[22:23], v[4:5]
	v_mov_b64_e32 v[20:21], v[2:3]
	v_mov_b64_e32 v[18:19], v[16:17]
	s_add_i32 s75, s23, 16
	s_lshr_b32 s76, s22, 6
	s_add_i32 s78, s39, 0x4000
	s_add_i32 s79, s38, 0x8000
	s_add_i32 s80, s80, 64
	v_add_u32_e32 v195, s23, v186
	s_mov_b32 s81, 0
	v_mov_b32_e32 v198, 0
	v_mov_b32_e32 v196, 0
	v_mov_b32_e32 v224, 0
	v_mov_b32_e32 v225, 0
	v_mov_b32_e32 v226, 0
	v_mov_b32_e32 v227, 0
	v_mov_b32_e32 v228, 0
	v_mov_b32_e32 v229, 0
	v_mov_b32_e32 v230, 0
	v_mov_b32_e32 v231, 0
	v_mov_b32_e32 v232, 0
	v_mov_b32_e32 v233, 0
	v_mov_b32_e32 v234, 0
	v_mov_b32_e32 v235, 0
	v_mov_b32_e32 v236, 0
	v_mov_b32_e32 v237, 0
	v_mov_b32_e32 v238, 0
	v_mov_b32_e32 v239, 0
	s_mov_b32 s82, 63
	v_mov_b64_e32 v[16:17], v[14:15]
	v_mov_b64_e32 v[14:15], v[12:13]
	v_mov_b64_e32 v[12:13], v[10:11]
	v_mov_b64_e32 v[10:11], v[8:9]
	v_mov_b64_e32 v[8:9], v[6:7]
	v_mov_b64_e32 v[6:7], v[4:5]
	v_mov_b64_e32 v[4:5], v[2:3]
	v_mov_b32_e32 v3, v183
	v_mov_b32_e32 v197, v184
	v_xor_b32_e32 v245, 0x20, v183
	v_xor_b32_e32 v246, 0x40, v183
	v_xor_b32_e32 v247, 0x60, v183
	v_xor_b32_e32 v248, 0x80, v183
	v_xor_b32_e32 v249, 0xa0, v183
	v_xor_b32_e32 v250, 0xc0, v183
	v_xor_b32_e32 v251, 0xe0, v183
	v_xor_b32_e32 v252, 0x20, v184
	v_xor_b32_e32 v253, 0x40, v184
	v_xor_b32_e32 v254, 0x60, v184
	s_mov_b32 s38, s77
	s_mov_b32 s83, 0
.LBB0_615:
	s_setprio 1
	s_cmp_eq_u32 s81, 0
	s_cselect_b64 s[56:57], -1, 0
	s_and_b64 vcc, exec, s[56:57]
	s_cbranch_vccnz .LBB0_617
	v_lshl_add_u32 v199, s83, 14, v182
	ds_read_b64_tr_b16 v[84:85], v199 offset:0x0
	ds_read_b64_tr_b16 v[86:87], v199 offset:0x800
	ds_read_b64_tr_b16 v[88:89], v199 offset:0x1000
	ds_read_b64_tr_b16 v[90:91], v199 offset:0x1800
	ds_read_b64_tr_b16 v[92:93], v199 offset:0x2000
	ds_read_b64_tr_b16 v[94:95], v199 offset:0x2800
	ds_read_b64_tr_b16 v[96:97], v199 offset:0x3000
	ds_read_b64_tr_b16 v[98:99], v199 offset:0x3800
	s_waitcnt lgkmcnt(6)
	v_mfma_f32_32x32x16_bf16 v[52:67], v[68:71], v[84:87], v[52:67]
	ds_read_b64_tr_b16 v[200:201], v199 offset:0x200
	ds_read_b64_tr_b16 v[202:203], v199 offset:0xa00
	s_waitcnt lgkmcnt(6)
	v_mfma_f32_32x32x16_bf16 v[52:67], v[72:75], v[88:91], v[52:67]
	ds_read_b64_tr_b16 v[204:205], v199 offset:0x1200
	ds_read_b64_tr_b16 v[206:207], v199 offset:0x1a00
	s_waitcnt lgkmcnt(6)
	v_mfma_f32_32x32x16_bf16 v[52:67], v[76:79], v[92:95], v[52:67]
	ds_read_b64_tr_b16 v[208:209], v199 offset:0x2200
	ds_read_b64_tr_b16 v[210:211], v199 offset:0x2a00
	s_waitcnt lgkmcnt(6)
	v_mfma_f32_32x32x16_bf16 v[52:67], v[80:83], v[96:99], v[52:67]
	ds_read_b64_tr_b16 v[212:213], v199 offset:0x3200
	ds_read_b64_tr_b16 v[214:215], v199 offset:0x3a00
	ds_read_b64_tr_b16 v[84:85], v199 offset:0x400
	ds_read_b64_tr_b16 v[86:87], v199 offset:0xc00
	s_waitcnt lgkmcnt(8)
	v_mfma_f32_32x32x16_bf16 v[36:51], v[68:71], v[200:203], v[36:51]
	ds_read_b64_tr_b16 v[88:89], v199 offset:0x1400
	ds_read_b64_tr_b16 v[90:91], v199 offset:0x1c00
	s_waitcnt lgkmcnt(8)
	v_mfma_f32_32x32x16_bf16 v[36:51], v[72:75], v[204:207], v[36:51]
	ds_read_b64_tr_b16 v[92:93], v199 offset:0x2400
	ds_read_b64_tr_b16 v[94:95], v199 offset:0x2c00
	s_waitcnt lgkmcnt(8)
	v_mfma_f32_32x32x16_bf16 v[36:51], v[76:79], v[208:211], v[36:51]
	ds_read_b64_tr_b16 v[96:97], v199 offset:0x3400
	ds_read_b64_tr_b16 v[98:99], v199 offset:0x3c00
	s_waitcnt lgkmcnt(8)
	v_mfma_f32_32x32x16_bf16 v[36:51], v[80:83], v[212:215], v[36:51]
	ds_read_b64_tr_b16 v[200:201], v199 offset:0x600
	ds_read_b64_tr_b16 v[202:203], v199 offset:0xe00
	s_waitcnt lgkmcnt(8)
	v_mfma_f32_32x32x16_bf16 v[20:35], v[68:71], v[84:87], v[20:35]
	ds_read_b64_tr_b16 v[204:205], v199 offset:0x1600
	ds_read_b64_tr_b16 v[206:207], v199 offset:0x1e00
	s_waitcnt lgkmcnt(8)
	v_mfma_f32_32x32x16_bf16 v[20:35], v[72:75], v[88:91], v[20:35]
	ds_read_b64_tr_b16 v[208:209], v199 offset:0x2600
	ds_read_b64_tr_b16 v[210:211], v199 offset:0x2e00
	s_waitcnt lgkmcnt(8)
	v_mfma_f32_32x32x16_bf16 v[20:35], v[76:79], v[92:95], v[20:35]
	ds_read_b64_tr_b16 v[212:213], v199 offset:0x3600
	ds_read_b64_tr_b16 v[214:215], v199 offset:0x3e00
	s_waitcnt lgkmcnt(8)
	v_mfma_f32_32x32x16_bf16 v[20:35], v[80:83], v[96:99], v[20:35]
	s_waitcnt lgkmcnt(6)
	v_mfma_f32_32x32x16_bf16 v[4:19], v[68:71], v[200:203], v[4:19]
	ds_read_b128 v[68:71], v3 offset:0x0
	s_waitcnt lgkmcnt(5)
	v_mfma_f32_32x32x16_bf16 v[4:19], v[72:75], v[204:207], v[4:19]
	ds_read_b128 v[72:75], v3 offset:0x2000
	ds_read_b128 v[200:203], v245 offset:0x0
	s_waitcnt lgkmcnt(5)
	v_mfma_f32_32x32x16_bf16 v[4:19], v[76:79], v[208:211], v[4:19]
	ds_read_b128 v[204:207], v245 offset:0x2000
	s_waitcnt lgkmcnt(4)
	v_mfma_f32_32x32x16_bf16 v[4:19], v[80:83], v[212:215], v[4:19]
	ds_read_b128 v[208:211], v246 offset:0x0
	ds_read_b128 v[212:215], v246 offset:0x2000
	s_branch .Lattn_qk
; #define SBAR() __builtin_amdgcn_sched_barrier(0)
; #define QK_RD(d0, sl) do { if ((d0) < 8) { const int a_ = kbase ^ (((d0) & 7) << 5); KRD(f0[sl], a_, 0); KRD(f1[sl], a_, 32 * 256); } \
;                            else { const int a_ = rbase ^ (((d0) & 3) << 5); KRD(f0[sl], a_, 0); KRD(f1[sl], a_, 32 * 128); } } while (0)
; #define LGKM(n) asm volatile("s_waitcnt lgkmcnt(" #n ")" ::: "memory")
; __device__ __forceinline__ void mphase(bool has_pv, f32x16* o, int vb, bf16x8 pa0, bf16x8 pa1, bf16x8 pa2, bf16x8 pa3, f32x16& p0, f32x16& p1, int kbase, int rbase, const bf16x8* qr) {
;     ...
;     QK_RD(0, 0); QK_RD(1, 1);
;     p0 = f32x16{}; p1 = f32x16{};
; #pragma unroll
;     for (int d0 = 0; d0 < 12; ++d0) {
;         if (d0 + 2 < 12) { QK_RD(d0 + 2, (d0 + 2) % 3); LGKM(4); }
;         else if (d0 + 1 < 12) LGKM(2);
;         else LGKM(0);
;         SBAR();
;         p0 = __builtin_amdgcn_mfma_f32_32x32x16_bf16(f0[d0 % 3], qr[d0], p0, 0, 0, 0);
;         p1 = __builtin_amdgcn_mfma_f32_32x32x16_bf16(f1[d0 % 3], qr[d0], p1, 0, 0, 0);
;         SBAR(); }
; __device__ __forceinline__ void attn_block(const Ptrs& P, int b, int h, int qb, LAS char* lds) {
;     ...
;         __builtin_amdgcn_s_setprio(0);
;         kbase ^= SHM_K; rbase ^= SHM_R;
;         __syncthreads();
;         { const int kb_ = x * KVBLK; if (kb_ + KVBLK - 1 > qlo) { const int dq = qm - kb_; const float NEG = -__builtin_inff();
; #pragma unroll
;             for (int r = 0; r < 16; ++r) { const int c_ = (r & 3) + 8 * (r >> 2); if (dq - c_ < 0) p0[r] = NEG; if (dq - c_ - 32 < 0) p1[r] = NEG; } } }
.LBB0_617:
	ds_read_b128 v[68:71], v3 offset:0x0
	ds_read_b128 v[72:75], v3 offset:0x2000
	ds_read_b128 v[200:203], v245 offset:0x0
	ds_read_b128 v[204:207], v245 offset:0x2000
	ds_read_b128 v[208:211], v246 offset:0x0
	ds_read_b128 v[212:215], v246 offset:0x2000
.Lattn_qk:
	s_waitcnt lgkmcnt(4)
	v_mfma_f32_32x32x16_bf16 v[84:99], v[68:71], v[100:103], v[224:239]
	v_mfma_f32_32x32x16_bf16 v[68:83], v[72:75], v[100:103], v[224:239]
	ds_read_b128 v[216:219], v247 offset:0x0
	ds_read_b128 v[220:223], v247 offset:0x2000
	s_waitcnt lgkmcnt(4)
	v_mfma_f32_32x32x16_bf16 v[84:99], v[200:203], v[104:107], v[84:99]
	v_mfma_f32_32x32x16_bf16 v[68:83], v[204:207], v[104:107], v[68:83]
	ds_read_b128 v[200:203], v248 offset:0x0
	ds_read_b128 v[204:207], v248 offset:0x2000
	s_waitcnt lgkmcnt(4)
	v_mfma_f32_32x32x16_bf16 v[84:99], v[208:211], v[108:111], v[84:99]
	v_mfma_f32_32x32x16_bf16 v[68:83], v[212:215], v[108:111], v[68:83]
	ds_read_b128 v[208:211], v249 offset:0x0
	ds_read_b128 v[212:215], v249 offset:0x2000
	s_waitcnt lgkmcnt(4)
	v_mfma_f32_32x32x16_bf16 v[84:99], v[216:219], v[112:115], v[84:99]
	v_mfma_f32_32x32x16_bf16 v[68:83], v[220:223], v[112:115], v[68:83]
	ds_read_b128 v[216:219], v250 offset:0x0
	ds_read_b128 v[220:223], v250 offset:0x2000
	s_waitcnt lgkmcnt(4)
	v_mfma_f32_32x32x16_bf16 v[84:99], v[200:203], v[116:119], v[84:99]
	v_mfma_f32_32x32x16_bf16 v[68:83], v[204:207], v[116:119], v[68:83]
	ds_read_b128 v[200:203], v251 offset:0x0
	ds_read_b128 v[204:207], v251 offset:0x2000
	s_waitcnt lgkmcnt(4)
	v_mfma_f32_32x32x16_bf16 v[84:99], v[208:211], v[120:123], v[84:99]
	v_mfma_f32_32x32x16_bf16 v[68:83], v[212:215], v[120:123], v[68:83]
	ds_read_b128 v[208:211], v197 offset:0x0
	ds_read_b128 v[212:215], v197 offset:0x1000
	s_waitcnt lgkmcnt(4)
	v_mfma_f32_32x32x16_bf16 v[84:99], v[216:219], v[124:127], v[84:99]
	v_mfma_f32_32x32x16_bf16 v[68:83], v[220:223], v[124:127], v[68:83]
	ds_read_b128 v[216:219], v252 offset:0x0
	ds_read_b128 v[220:223], v252 offset:0x1000
	s_waitcnt lgkmcnt(4)
	v_mfma_f32_32x32x16_bf16 v[84:99], v[200:203], v[128:131], v[84:99]
	v_mfma_f32_32x32x16_bf16 v[68:83], v[204:207], v[128:131], v[68:83]
	ds_read_b128 v[200:203], v253 offset:0x0
	ds_read_b128 v[204:207], v253 offset:0x1000
	s_waitcnt lgkmcnt(4)
	v_mfma_f32_32x32x16_bf16 v[84:99], v[208:211], v[132:135], v[84:99]
	v_mfma_f32_32x32x16_bf16 v[68:83], v[212:215], v[132:135], v[68:83]
	ds_read_b128 v[208:211], v254 offset:0x0
	ds_read_b128 v[212:215], v254 offset:0x1000
	s_waitcnt lgkmcnt(4)
	v_mfma_f32_32x32x16_bf16 v[84:99], v[216:219], v[136:139], v[84:99]
	v_mfma_f32_32x32x16_bf16 v[68:83], v[220:223], v[136:139], v[68:83]
	s_waitcnt lgkmcnt(2)
	v_mfma_f32_32x32x16_bf16 v[84:99], v[200:203], v[140:143], v[84:99]
	v_mfma_f32_32x32x16_bf16 v[68:83], v[204:207], v[140:143], v[68:83]
	s_waitcnt lgkmcnt(0)
	v_mfma_f32_32x32x16_bf16 v[84:99], v[208:211], v[144:147], v[84:99]
	v_mfma_f32_32x32x16_bf16 v[68:83], v[212:215], v[144:147], v[68:83]
	s_setprio 0
	s_cmp_le_u32 s82, s75
	s_barrier
	s_cbranch_scc1 .LBB0_619
	v_add_u32_e32 v199, s81, v195
	s_nop 3
	v_cmp_gt_i32_e64 s[22:23], -16, v199
	v_cmp_gt_i32_e64 s[98:99], 16, v199
	v_cmp_gt_i32_e64 s[100:101], -15, v199
	v_cmp_gt_i32_e64 vcc, 17, v199
	v_cndmask_b32_e64 v84, v84, v191, s[22:23]
	v_cndmask_b32_e64 v68, v68, v191, s[98:99]
	v_cndmask_b32_e64 v85, v85, v191, s[100:101]
	v_cndmask_b32_e64 v69, v69, v191, vcc
	v_cmp_gt_i32_e64 s[22:23], -14, v199
	v_cmp_gt_i32_e64 s[98:99], 18, v199
	v_cmp_gt_i32_e64 s[100:101], -13, v199
	v_cmp_gt_i32_e64 vcc, 19, v199
	v_cndmask_b32_e64 v86, v86, v191, s[22:23]
	v_cndmask_b32_e64 v70, v70, v191, s[98:99]
	v_cndmask_b32_e64 v87, v87, v191, s[100:101]
	v_cndmask_b32_e64 v71, v71, v191, vcc
	v_cmp_gt_i32_e64 s[22:23], -8, v199
	v_cmp_gt_i32_e64 s[98:99], 24, v199
	v_cmp_gt_i32_e64 s[100:101], -7, v199
	v_cmp_gt_i32_e64 vcc, 25, v199
	v_cndmask_b32_e64 v88, v88, v191, s[22:23]
	v_cndmask_b32_e64 v72, v72, v191, s[98:99]
	v_cndmask_b32_e64 v89, v89, v191, s[100:101]
	v_cndmask_b32_e64 v73, v73, v191, vcc
	v_cmp_gt_i32_e64 s[22:23], -6, v199
	v_cmp_gt_i32_e64 s[98:99], 26, v199
	v_cmp_gt_i32_e64 s[100:101], -5, v199
	v_cmp_gt_i32_e64 vcc, 27, v199
	v_cndmask_b32_e64 v90, v90, v191, s[22:23]
	v_cndmask_b32_e64 v74, v74, v191, s[98:99]
	v_cndmask_b32_e64 v91, v91, v191, s[100:101]
	v_cndmask_b32_e64 v75, v75, v191, vcc
	v_cmp_gt_i32_e64 s[22:23], 0, v199
	v_cmp_gt_i32_e64 s[98:99], 32, v199
	v_cmp_gt_i32_e64 s[100:101], 1, v199
	v_cmp_gt_i32_e64 vcc, 33, v199
	v_cndmask_b32_e64 v92, v92, v191, s[22:23]
	v_cndmask_b32_e64 v76, v76, v191, s[98:99]
	v_cndmask_b32_e64 v93, v93, v191, s[100:101]
	v_cndmask_b32_e64 v77, v77, v191, vcc
	v_cmp_gt_i32_e64 s[22:23], 2, v199
	v_cmp_gt_i32_e64 s[98:99], 34, v199
	v_cmp_gt_i32_e64 s[100:101], 3, v199
	v_cmp_gt_i32_e64 vcc, 35, v199
	v_cndmask_b32_e64 v94, v94, v191, s[22:23]
	v_cndmask_b32_e64 v78, v78, v191, s[98:99]
	v_cndmask_b32_e64 v95, v95, v191, s[100:101]
	v_cndmask_b32_e64 v79, v79, v191, vcc
	v_cmp_gt_i32_e64 s[22:23], 8, v199
	v_cmp_gt_i32_e64 s[98:99], 40, v199
	v_cmp_gt_i32_e64 s[100:101], 9, v199
	v_cmp_gt_i32_e64 vcc, 41, v199
	v_cndmask_b32_e64 v96, v96, v191, s[22:23]
	v_cndmask_b32_e64 v80, v80, v191, s[98:99]
	v_cndmask_b32_e64 v97, v97, v191, s[100:101]
	v_cndmask_b32_e64 v81, v81, v191, vcc
	v_cmp_gt_i32_e64 s[22:23], 10, v199
	v_cmp_gt_i32_e64 s[98:99], 42, v199
	v_cmp_gt_i32_e64 s[100:101], 11, v199
	v_cmp_gt_i32_e64 vcc, 43, v199
	v_cndmask_b32_e64 v98, v98, v191, s[22:23]
	v_cndmask_b32_e64 v82, v82, v191, s[98:99]
	v_cndmask_b32_e64 v99, v99, v191, s[100:101]
	v_cndmask_b32_e64 v83, v83, v191, vcc

; #define SBAR() __builtin_amdgcn_sched_barrier(0)
; #define QK_RD(d0, sl) do { if ((d0) < 8) { const int a_ = kbase ^ (((d0) & 7) << 5); KRD(f0[sl], a_, 0); KRD(f1[sl], a_, 32 * 256); } \
;                            else { const int a_ = rbase ^ (((d0) & 3) << 5); KRD(f0[sl], a_, 0); KRD(f1[sl], a_, 32 * 128); } } while (0)
; #define PV_RD(d0, L, H) do { constexpr int b_ = v_rd_off(d0, 0, 0); TRRD(L[0], b_); TRRD(H[0], b_ + 2048); TRRD(L[1], b_ + 4096); TRRD(H[1], b_ + 6144); TRRD(L[2], b_ + 8192); TRRD(H[2], b_ + 10240); TRRD(L[3], b_ + 12288); TRRD(H[3], b_ + 14336); } while (0)
; #define LGKM(n) asm volatile("s_waitcnt lgkmcnt(" #n ")" ::: "memory")
; __device__ __forceinline__ void mphase(bool has_pv, f32x16* o, int vb, bf16x8 pa0, bf16x8 pa1, bf16x8 pa2, bf16x8 pa3, f32x16& p0, f32x16& p1, int kbase, int rbase, const bf16x8* qr) {
;     ...
;     if (has_pv) {
;         s16x4 la[4], ha[4], lb[4], hb[4];
;         PV_RD(0, la, ha); PV_RD(1, lb, hb);
;         LGKM(8); SBAR(); PV_MM(0, la, ha); SBAR();
;         PV_RD(2, la, ha); LGKM(8); SBAR(); PV_MM(1, lb, hb); SBAR();
;         PV_RD(3, lb, hb); LGKM(8); SBAR(); PV_MM(2, la, ha); SBAR();
;         LGKM(0); SBAR(); PV_MM(3, lb, hb); SBAR();
;     }
;     QK_RD(0, 0); QK_RD(1, 1);
;     p0 = f32x16{}; p1 = f32x16{};
; #pragma unroll
;     for (int d0 = 0; d0 < 12; ++d0) {
;         if (d0 + 2 < 12) { QK_RD(d0 + 2, (d0 + 2) % 3); LGKM(4); }
.Lattn_odd_b615:
	s_setprio 1
	s_cmp_eq_u32 s81, 0
	s_cselect_b64 s[56:57], -1, 0
	s_and_b64 vcc, exec, s[56:57]
	s_cbranch_vccnz .Lattn_odd_b617
	v_lshl_add_u32 v199, s83, 14, v182
	ds_read_b64_tr_b16 v[84:85], v199 offset:0x0
	ds_read_b64_tr_b16 v[86:87], v199 offset:0x800
	ds_read_b64_tr_b16 v[88:89], v199 offset:0x1000
	ds_read_b64_tr_b16 v[90:91], v199 offset:0x1800
	ds_read_b64_tr_b16 v[92:93], v199 offset:0x2000
	ds_read_b64_tr_b16 v[94:95], v199 offset:0x2800
	ds_read_b64_tr_b16 v[96:97], v199 offset:0x3000
	ds_read_b64_tr_b16 v[98:99], v199 offset:0x3800
	s_waitcnt lgkmcnt(6)
	v_mfma_f32_32x32x16_bf16 v[52:67], v[68:71], v[84:87], v[52:67]
	ds_read_b64_tr_b16 v[200:201], v199 offset:0x200
	ds_read_b64_tr_b16 v[202:203], v199 offset:0xa00
	s_waitcnt lgkmcnt(6)
	v_mfma_f32_32x32x16_bf16 v[52:67], v[72:75], v[88:91], v[52:67]
	ds_read_b64_tr_b16 v[204:205], v199 offset:0x1200
	ds_read_b64_tr_b16 v[206:207], v199 offset:0x1a00
	s_waitcnt lgkmcnt(6)
	v_mfma_f32_32x32x16_bf16 v[52:67], v[76:79], v[92:95], v[52:67]
	ds_read_b64_tr_b16 v[208:209], v199 offset:0x2200
	ds_read_b64_tr_b16 v[210:211], v199 offset:0x2a00
	s_waitcnt lgkmcnt(6)
	v_mfma_f32_32x32x16_bf16 v[52:67], v[80:83], v[96:99], v[52:67]
	ds_read_b64_tr_b16 v[212:213], v199 offset:0x3200
	ds_read_b64_tr_b16 v[214:215], v199 offset:0x3a00
	ds_read_b64_tr_b16 v[84:85], v199 offset:0x400
	ds_read_b64_tr_b16 v[86:87], v199 offset:0xc00
	s_waitcnt lgkmcnt(8)
	v_mfma_f32_32x32x16_bf16 v[36:51], v[68:71], v[200:203], v[36:51]
	ds_read_b64_tr_b16 v[88:89], v199 offset:0x1400
	ds_read_b64_tr_b16 v[90:91], v199 offset:0x1c00
	s_waitcnt lgkmcnt(8)
	v_mfma_f32_32x32x16_bf16 v[36:51], v[72:75], v[204:207], v[36:51]
	ds_read_b64_tr_b16 v[92:93], v199 offset:0x2400
	ds_read_b64_tr_b16 v[94:95], v199 offset:0x2c00
	s_waitcnt lgkmcnt(8)
	v_mfma_f32_32x32x16_bf16 v[36:51], v[76:79], v[208:211], v[36:51]
	ds_read_b64_tr_b16 v[96:97], v199 offset:0x3400
	ds_read_b64_tr_b16 v[98:99], v199 offset:0x3c00
	s_waitcnt lgkmcnt(8)
	v_mfma_f32_32x32x16_bf16 v[36:51], v[80:83], v[212:215], v[36:51]
	ds_read_b64_tr_b16 v[200:201], v199 offset:0x600
	ds_read_b64_tr_b16 v[202:203], v199 offset:0xe00
	s_waitcnt lgkmcnt(8)
	v_mfma_f32_32x32x16_bf16 v[20:35], v[68:71], v[84:87], v[20:35]
	ds_read_b64_tr_b16 v[204:205], v199 offset:0x1600
	ds_read_b64_tr_b16 v[206:207], v199 offset:0x1e00
	s_waitcnt lgkmcnt(8)
	v_mfma_f32_32x32x16_bf16 v[20:35], v[72:75], v[88:91], v[20:35]
	ds_read_b64_tr_b16 v[208:209], v199 offset:0x2600
	ds_read_b64_tr_b16 v[210:211], v199 offset:0x2e00
	s_waitcnt lgkmcnt(8)
	v_mfma_f32_32x32x16_bf16 v[20:35], v[76:79], v[92:95], v[20:35]
	ds_read_b64_tr_b16 v[212:213], v199 offset:0x3600
	ds_read_b64_tr_b16 v[214:215], v199 offset:0x3e00
	s_waitcnt lgkmcnt(8)
	v_mfma_f32_32x32x16_bf16 v[20:35], v[80:83], v[96:99], v[20:35]
	s_waitcnt lgkmcnt(6)
	v_mfma_f32_32x32x16_bf16 v[4:19], v[68:71], v[200:203], v[4:19]
	ds_read_b128 v[68:71], v3 offset:0x4000
	s_waitcnt lgkmcnt(5)
	v_mfma_f32_32x32x16_bf16 v[4:19], v[72:75], v[204:207], v[4:19]
	ds_read_b128 v[72:75], v3 offset:0x6000
	ds_read_b128 v[200:203], v245 offset:0x4000
	s_waitcnt lgkmcnt(5)
	v_mfma_f32_32x32x16_bf16 v[4:19], v[76:79], v[208:211], v[4:19]
	ds_read_b128 v[204:207], v245 offset:0x6000
	s_waitcnt lgkmcnt(4)
	v_mfma_f32_32x32x16_bf16 v[4:19], v[80:83], v[212:215], v[4:19]
	ds_read_b128 v[208:211], v246 offset:0x4000
	ds_read_b128 v[212:215], v246 offset:0x6000
	s_branch .Lattn_odd_aqk
.Lattn_odd_b617:
	ds_read_b128 v[68:71], v3 offset:0x4000
	ds_read_b128 v[72:75], v3 offset:0x6000
	ds_read_b128 v[200:203], v245 offset:0x4000
	ds_read_b128 v[204:207], v245 offset:0x6000
	ds_read_b128 v[208:211], v246 offset:0x4000
	ds_read_b128 v[212:215], v246 offset:0x6000
; #define SBAR() __builtin_amdgcn_sched_barrier(0)
; #define QK_RD(d0, sl) do { if ((d0) < 8) { const int a_ = kbase ^ (((d0) & 7) << 5); KRD(f0[sl], a_, 0); KRD(f1[sl], a_, 32 * 256); } \
;                            else { const int a_ = rbase ^ (((d0) & 3) << 5); KRD(f0[sl], a_, 0); KRD(f1[sl], a_, 32 * 128); } } while (0)
; #define LGKM(n) asm volatile("s_waitcnt lgkmcnt(" #n ")" ::: "memory")
; __device__ __forceinline__ void mphase(bool has_pv, f32x16* o, int vb, bf16x8 pa0, bf16x8 pa1, bf16x8 pa2, bf16x8 pa3, f32x16& p0, f32x16& p1, int kbase, int rbase, const bf16x8* qr) {
;     ...
;     QK_RD(0, 0); QK_RD(1, 1);
;     p0 = f32x16{}; p1 = f32x16{};
; #pragma unroll
;     for (int d0 = 0; d0 < 12; ++d0) {
;         if (d0 + 2 < 12) { QK_RD(d0 + 2, (d0 + 2) % 3); LGKM(4); }
;         else if (d0 + 1 < 12) LGKM(2);
;         else LGKM(0);
;         SBAR();
;         p0 = __builtin_amdgcn_mfma_f32_32x32x16_bf16(f0[d0 % 3], qr[d0], p0, 0, 0, 0);
;         p1 = __builtin_amdgcn_mfma_f32_32x32x16_bf16(f1[d0 % 3], qr[d0], p1, 0, 0, 0);
;         SBAR(); }
; __device__ __forceinline__ void attn_block(const Ptrs& P, int b, int h, int qb, LAS char* lds) {
;     ...
;         __syncthreads();
;         { const int kb_ = x * KVBLK; if (kb_ + KVBLK - 1 > qlo) { const int dq = qm - kb_; const float NEG = -__builtin_inff();
; #pragma unroll
;             for (int r = 0; r < 16; ++r) { const int c_ = (r & 3) + 8 * (r >> 2); if (dq - c_ < 0) p0[r] = NEG; if (dq - c_ - 32 < 0) p1[r] = NEG; } } }
.Lattn_odd_aqk:
	s_waitcnt lgkmcnt(4)
	v_mfma_f32_32x32x16_bf16 v[84:99], v[68:71], v[100:103], v[224:239]
	v_mfma_f32_32x32x16_bf16 v[68:83], v[72:75], v[100:103], v[224:239]
	ds_read_b128 v[216:219], v247 offset:0x4000
	ds_read_b128 v[220:223], v247 offset:0x6000
	s_waitcnt lgkmcnt(4)
	v_mfma_f32_32x32x16_bf16 v[84:99], v[200:203], v[104:107], v[84:99]
	v_mfma_f32_32x32x16_bf16 v[68:83], v[204:207], v[104:107], v[68:83]
	ds_read_b128 v[200:203], v248 offset:0x4000
	ds_read_b128 v[204:207], v248 offset:0x6000
	s_waitcnt lgkmcnt(4)
	v_mfma_f32_32x32x16_bf16 v[84:99], v[208:211], v[108:111], v[84:99]
	v_mfma_f32_32x32x16_bf16 v[68:83], v[212:215], v[108:111], v[68:83]
	ds_read_b128 v[208:211], v249 offset:0x4000
	ds_read_b128 v[212:215], v249 offset:0x6000
	s_waitcnt lgkmcnt(4)
	v_mfma_f32_32x32x16_bf16 v[84:99], v[216:219], v[112:115], v[84:99]
	v_mfma_f32_32x32x16_bf16 v[68:83], v[220:223], v[112:115], v[68:83]
	ds_read_b128 v[216:219], v250 offset:0x4000
	ds_read_b128 v[220:223], v250 offset:0x6000
	s_waitcnt lgkmcnt(4)
	v_mfma_f32_32x32x16_bf16 v[84:99], v[200:203], v[116:119], v[84:99]
	v_mfma_f32_32x32x16_bf16 v[68:83], v[204:207], v[116:119], v[68:83]
	ds_read_b128 v[200:203], v251 offset:0x4000
	ds_read_b128 v[204:207], v251 offset:0x6000
	s_waitcnt lgkmcnt(4)
	v_mfma_f32_32x32x16_bf16 v[84:99], v[208:211], v[120:123], v[84:99]
	v_mfma_f32_32x32x16_bf16 v[68:83], v[212:215], v[120:123], v[68:83]
	ds_read_b128 v[208:211], v197 offset:0x2000
	ds_read_b128 v[212:215], v197 offset:0x3000
	s_waitcnt lgkmcnt(4)
	v_mfma_f32_32x32x16_bf16 v[84:99], v[216:219], v[124:127], v[84:99]
	v_mfma_f32_32x32x16_bf16 v[68:83], v[220:223], v[124:127], v[68:83]
	ds_read_b128 v[216:219], v252 offset:0x2000
	ds_read_b128 v[220:223], v252 offset:0x3000
	s_waitcnt lgkmcnt(4)
	v_mfma_f32_32x32x16_bf16 v[84:99], v[200:203], v[128:131], v[84:99]
	v_mfma_f32_32x32x16_bf16 v[68:83], v[204:207], v[128:131], v[68:83]
	ds_read_b128 v[200:203], v253 offset:0x2000
	ds_read_b128 v[204:207], v253 offset:0x3000
	s_waitcnt lgkmcnt(4)
	v_mfma_f32_32x32x16_bf16 v[84:99], v[208:211], v[132:135], v[84:99]
	v_mfma_f32_32x32x16_bf16 v[68:83], v[212:215], v[132:135], v[68:83]
	ds_read_b128 v[208:211], v254 offset:0x2000
	ds_read_b128 v[212:215], v254 offset:0x3000
	s_waitcnt lgkmcnt(4)
	v_mfma_f32_32x32x16_bf16 v[84:99], v[216:219], v[136:139], v[84:99]
	v_mfma_f32_32x32x16_bf16 v[68:83], v[220:223], v[136:139], v[68:83]
	s_waitcnt lgkmcnt(2)
	v_mfma_f32_32x32x16_bf16 v[84:99], v[200:203], v[140:143], v[84:99]
	v_mfma_f32_32x32x16_bf16 v[68:83], v[204:207], v[140:143], v[68:83]
	s_waitcnt lgkmcnt(0)
	v_mfma_f32_32x32x16_bf16 v[84:99], v[208:211], v[144:147], v[84:99]
	v_mfma_f32_32x32x16_bf16 v[68:83], v[212:215], v[144:147], v[68:83]
	s_setprio 0
	s_cmp_le_u32 s82, s75
	s_barrier
	s_cbranch_scc1 .Lattn_odd_b619
	v_add_u32_e32 v199, s81, v195
	s_nop 3
	v_cmp_gt_i32_e64 s[22:23], -16, v199
	v_cmp_gt_i32_e64 s[98:99], 16, v199
	v_cmp_gt_i32_e64 s[100:101], -15, v199
	v_cmp_gt_i32_e64 vcc, 17, v199
	v_cndmask_b32_e64 v84, v84, v191, s[22:23]
	v_cndmask_b32_e64 v68, v68, v191, s[98:99]
	v_cndmask_b32_e64 v85, v85, v191, s[100:101]
	v_cndmask_b32_e64 v69, v69, v191, vcc
	v_cmp_gt_i32_e64 s[22:23], -14, v199
	v_cmp_gt_i32_e64 s[98:99], 18, v199
	v_cmp_gt_i32_e64 s[100:101], -13, v199
	v_cmp_gt_i32_e64 vcc, 19, v199
	v_cndmask_b32_e64 v86, v86, v191, s[22:23]
	v_cndmask_b32_e64 v70, v70, v191, s[98:99]
	v_cndmask_b32_e64 v87, v87, v191, s[100:101]
	v_cndmask_b32_e64 v71, v71, v191, vcc
	v_cmp_gt_i32_e64 s[22:23], -8, v199
	v_cmp_gt_i32_e64 s[98:99], 24, v199
	v_cmp_gt_i32_e64 s[100:101], -7, v199
	v_cmp_gt_i32_e64 vcc, 25, v199
	v_cndmask_b32_e64 v88, v88, v191, s[22:23]
	v_cndmask_b32_e64 v72, v72, v191, s[98:99]
	v_cndmask_b32_e64 v89, v89, v191, s[100:101]
	v_cndmask_b32_e64 v73, v73, v191, vcc
	v_cmp_gt_i32_e64 s[22:23], -6, v199
	v_cmp_gt_i32_e64 s[98:99], 26, v199
	v_cmp_gt_i32_e64 s[100:101], -5, v199
	v_cmp_gt_i32_e64 vcc, 27, v199
	v_cndmask_b32_e64 v90, v90, v191, s[22:23]
	v_cndmask_b32_e64 v74, v74, v191, s[98:99]
	v_cndmask_b32_e64 v91, v91, v191, s[100:101]
	v_cndmask_b32_e64 v75, v75, v191, vcc
	v_cmp_gt_i32_e64 s[22:23], 0, v199
	v_cmp_gt_i32_e64 s[98:99], 32, v199
	v_cmp_gt_i32_e64 s[100:101], 1, v199
	v_cmp_gt_i32_e64 vcc, 33, v199
	v_cndmask_b32_e64 v92, v92, v191, s[22:23]
	v_cndmask_b32_e64 v76, v76, v191, s[98:99]
	v_cndmask_b32_e64 v93, v93, v191, s[100:101]
	v_cndmask_b32_e64 v77, v77, v191, vcc
	v_cmp_gt_i32_e64 s[22:23], 2, v199
	v_cmp_gt_i32_e64 s[98:99], 34, v199
	v_cmp_gt_i32_e64 s[100:101], 3, v199
	v_cmp_gt_i32_e64 vcc, 35, v199
	v_cndmask_b32_e64 v94, v94, v191, s[22:23]
	v_cndmask_b32_e64 v78, v78, v191, s[98:99]
	v_cndmask_b32_e64 v95, v95, v191, s[100:101]
	v_cndmask_b32_e64 v79, v79, v191, vcc
	v_cmp_gt_i32_e64 s[22:23], 8, v199
	v_cmp_gt_i32_e64 s[98:99], 40, v199
	v_cmp_gt_i32_e64 s[100:101], 9, v199
	v_cmp_gt_i32_e64 vcc, 41, v199
	v_cndmask_b32_e64 v96, v96, v191, s[22:23]
	v_cndmask_b32_e64 v80, v80, v191, s[98:99]
	v_cndmask_b32_e64 v97, v97, v191, s[100:101]
	v_cndmask_b32_e64 v81, v81, v191, vcc
	v_cmp_gt_i32_e64 s[22:23], 10, v199
	v_cmp_gt_i32_e64 s[98:99], 42, v199
	v_cmp_gt_i32_e64 s[100:101], 11, v199
	v_cmp_gt_i32_e64 vcc, 43, v199
	v_cndmask_b32_e64 v98, v98, v191, s[22:23]
	v_cndmask_b32_e64 v82, v82, v191, s[98:99]
	v_cndmask_b32_e64 v99, v99, v191, s[100:101]
	v_cndmask_b32_e64 v83, v83, v191, vcc
